# seam 0: XCD-hierarchical barrier instead of cooperative-groups grid sync
# speedup vs baseline: 1.0039x; 1.0039x over previous
.LBB0_43:
	s_waitcnt lgkmcnt(0)
	s_cmp_gt_i32 s77, 1
	s_cselect_b64 s[8:9], -1, 0
	s_and_b64 s[4:5], s[20:21], s[8:9]
	s_andn2_b64 vcc, exec, s[4:5]
	s_cbranch_vccnz .LBB0_55
	s_mov_b64 s[46:47], s[8:9]
	s_waitcnt vmcnt(0)
	s_waitcnt lgkmcnt(0)
	s_barrier
	s_and_saveexec_b64 s[48:49], s[82:83]
	s_cbranch_execz .Lx0_115
	s_add_i32 s3, 0, 0x20000
	v_mov_b32_e32 v0, s3
	s_waitcnt vmcnt(0) expcnt(0) lgkmcnt(0)
	ds_read_b32 v2, v0
	s_add_i32 s3, 0, 0x20004
	v_mov_b32_e32 v0, s3
	ds_read_b32 v0, v0
	s_waitcnt lgkmcnt(1)
	v_cmp_ne_u32_e32 vcc, 0, v2
	s_cbranch_vccnz .Lx0_86
	s_add_u32 s6, s42, 0x51fda00
	s_addc_u32 s7, s43, 0
	s_add_u32 s10, s42, 0x51fdc00
	s_addc_u32 s11, s43, 0
	s_add_u32 s12, s42, 0x51fdd00
	s_addc_u32 s13, s43, 0
	s_add_u32 s14, s42, 0x51fde00
	s_addc_u32 s15, s43, 0
	s_add_u32 s16, s42, 0x51fdf00
	s_addc_u32 s17, s43, 0
	s_add_u32 s18, s42, 0x51fe000
	s_addc_u32 s19, s43, 0
	s_add_u32 s20, s42, 0x51fe100
	s_addc_u32 s21, s43, 0
	s_add_u32 s22, s42, 0x51fe200
	s_addc_u32 s23, s43, 0
	s_add_u32 s24, s42, 0x51fe300
	s_addc_u32 s25, s43, 0
	s_add_u32 s26, s42, 0x51fe400
	s_addc_u32 s27, s43, 0
	s_add_u32 s28, s42, 0x51fe500
	s_addc_u32 s29, s43, 0
	s_add_u32 s30, s42, 0x51fe600
	s_addc_u32 s31, s43, 0
	s_add_u32 s34, s42, 0x51fe700
	s_addc_u32 s35, s43, 0
	s_add_u32 s36, s42, 0x51fe800
	s_addc_u32 s37, s43, 0
	s_load_dwordx2 s[4:5], s[80:81], 0x4
	s_add_u32 s40, s42, 0x51fe900
	s_addc_u32 s41, s43, 0
	s_add_u32 s44, s42, 0x51fea00
	s_addc_u32 s45, s43, 0
	s_add_u32 s50, s42, 0x51feb00
	s_waitcnt lgkmcnt(0)
	s_mul_i32 s3, s4, s38
	s_addc_u32 s51, s43, 0
	s_mul_i32 s3, s3, s5
	s_mov_b32 s4, 1
	s_mov_b64 s[8:9], 0
	v_mov_b64_e32 v[0:1], s[10:11]
	v_mov_b64_e32 v[2:3], s[12:13]
	v_mov_b64_e32 v[4:5], s[14:15]
	v_mov_b64_e32 v[6:7], s[16:17]
	v_mov_b64_e32 v[8:9], s[18:19]
	v_mov_b64_e32 v[10:11], s[20:21]
	v_mov_b64_e32 v[12:13], s[22:23]
	v_mov_b64_e32 v[14:15], s[24:25]
	v_mov_b64_e32 v[16:17], s[26:27]
	v_mov_b64_e32 v[18:19], s[28:29]
	v_mov_b64_e32 v[20:21], s[30:31]
	v_mov_b64_e32 v[22:23], s[34:35]
	v_mov_b64_e32 v[24:25], s[36:37]
	v_mov_b64_e32 v[26:27], s[40:41]
	v_mov_b64_e32 v[28:29], s[44:45]
	v_mov_b64_e32 v[30:31], s[50:51]
	s_branch .Lx0_76

.Lx0_115:
	s_or_b64 exec, exec, s[48:49]
	s_waitcnt lgkmcnt(0)
	s_barrier
	s_mov_b64 s[8:9], s[46:47]
